# phase-0 rmsnorm row loop: next-row loads and both gain vectors issued at the iteration top, compute waits only for gains, next row waited at the loop bottom
# speedup vs baseline: 1.0024x; 1.0024x over previous
.LBB0_971:
	s_or_b64 exec, exec, s[2:3]
	s_mov_b32 s2, 0xd3ff
	v_cmp_lt_i32_e32 vcc, s2, v32
	s_waitcnt vmcnt(2)
	v_mov_b64_e32 v[0:1], v[86:87]
	v_mov_b64_e32 v[4:5], v[90:91]
	v_mov_b64_e32 v[8:9], v[78:79]
	v_mov_b64_e32 v[12:13], v[82:83]
	s_or_b64 s[6:7], vcc, s[6:7]
	v_mov_b64_e32 v[50:51], v[44:45]
	v_mov_b64_e32 v[38:39], v[46:47]
	v_mov_b64_e32 v[48:49], v[42:43]
	v_mov_b64_e32 v[36:37], v[40:41]
	v_mov_b64_e32 v[2:3], v[88:89]
	v_mov_b64_e32 v[6:7], v[92:93]
	v_mov_b64_e32 v[10:11], v[80:81]
	v_mov_b64_e32 v[14:15], v[84:85]
	s_andn2_b64 exec, exec, s[6:7]
	s_cbranch_execz .LBB0_986

.LBB0_984:
	s_or_b64 exec, exec, s[2:3]
	v_lshlrev_b32_e32 v176, 2, v34
	v_lshl_add_u64 v[60:61], v[50:51], 0, v[176:177]
	v_lshl_add_u64 v[74:75], v[16:17], 0, v[176:177]
	global_load_dwordx4 v[52:55], v[60:61], off
	global_load_dwordx4 v[56:59], v[60:61], off offset:16
	global_load_dwordx4 v[66:69], v[60:61], off offset:2048
	global_load_dwordx4 v[70:73], v[60:61], off offset:2064
	global_load_dwordx4 v[78:81], v[74:75], off offset:16
	global_load_dwordx4 v[82:85], v[74:75], off
	global_load_dwordx4 v[86:89], v[74:75], off offset:2064
	global_load_dwordx4 v[90:93], v[74:75], off offset:2048
	s_waitcnt vmcnt(4)
	v_mul_f32_e32 v18, v13, v13
	v_mul_f32_e32 v19, v9, v9
	v_mul_f32_e32 v20, v5, v5
	v_fmac_f32_e32 v18, v12, v12
	v_fmac_f32_e32 v19, v8, v8
	v_mul_f32_e32 v21, v1, v1
	v_fmac_f32_e32 v20, v4, v4
	v_fmac_f32_e32 v18, v14, v14
	v_fmac_f32_e32 v19, v10, v10
	v_fmac_f32_e32 v21, v0, v0
	v_fmac_f32_e32 v20, v6, v6
	v_fmac_f32_e32 v18, v15, v15
	v_fmac_f32_e32 v19, v11, v11
	v_fmac_f32_e32 v21, v2, v2
	v_fmac_f32_e32 v20, v7, v7
	v_add_f32_e32 v16, v18, v19
	v_fmac_f32_e32 v21, v3, v3
	v_add_f32_e32 v16, v16, v20
	v_add_f32_e32 v16, v16, v21
	v_lshlrev_b32_e32 v50, 1, v34
	v_mov_b32_e32 v51, v177
	v_add_f32_dpp v16, v16, v16 quad_perm:[1,0,3,2] row_mask:0xf bank_mask:0xf bound_ctrl:1
	v_lshl_add_u64 v[62:63], v[48:49], 0, v[50:51]
	s_nop 0
	v_add_f32_dpp v16, v16, v16 quad_perm:[2,3,0,1] row_mask:0xf bank_mask:0xf bound_ctrl:1
	s_nop 1
	v_add_f32_dpp v16, v16, v16 row_half_mirror row_mask:0xf bank_mask:0xf bound_ctrl:1
	s_nop 1
	v_add_f32_dpp v16, v16, v16 row_mirror row_mask:0xf bank_mask:0xf bound_ctrl:1
	v_mov_b32_e32 v17, v16
	s_nop 1
	v_permlane16_swap_b32_e32 v16, v17
	v_add_f32_e32 v16, v16, v17
	v_mov_b32_e32 v17, v16
	s_nop 1
	v_permlane32_swap_b32_e32 v16, v17
	v_add_f32_e32 v16, v16, v17
	v_fmamk_f32 v16, v16, 0x3a800000, v230
	v_mul_f32_e32 v17, 0x4b800000, v16
	v_cmp_gt_f32_e32 vcc, s91, v16
	s_nop 1
	v_cndmask_b32_e32 v16, v16, v17, vcc
	v_rsq_f32_e32 v33, v16
	s_nop 0
	v_mul_f32_e32 v35, 0x45800000, v33
	v_cndmask_b32_e32 v64, v33, v35, vcc
	v_mul_f32_e32 v48, v12, v64
	v_mul_f32_e32 v49, v13, v64
	v_mul_f32_e32 v14, v14, v64
	v_mul_f32_e32 v15, v15, v64
	v_mul_f32_e32 v12, v8, v64
	v_mul_f32_e32 v13, v9, v64
	v_mul_f32_e32 v10, v10, v64
	v_mul_f32_e32 v11, v11, v64
	v_mul_f32_e32 v6, v6, v64
	v_mul_f32_e32 v7, v7, v64
	v_cmp_ne_u64_e32 vcc, 0, v[38:39]
	v_mul_f32_e32 v8, v52, v48
	v_mul_f32_e32 v9, v53, v49
	v_mul_f32_e32 v54, v54, v14
	v_mul_f32_e32 v55, v55, v15
	v_mul_f32_e32 v56, v56, v12
	v_mul_f32_e32 v57, v57, v13
	v_mul_f32_e32 v58, v58, v10
	v_mul_f32_e32 v59, v59, v11
	v_cvt_pk_bf16_f32 v52, v8, v9
	v_cvt_pk_bf16_f32 v53, v54, v55
	v_cvt_pk_bf16_f32 v54, v56, v57
	v_cvt_pk_bf16_f32 v55, v58, v59
	global_store_dwordx4 v[62:63], v[52:55], off
	v_mul_f32_e32 v8, v4, v64
	v_mul_f32_e32 v9, v5, v64
	v_mul_f32_e32 v4, v0, v64
	v_mul_f32_e32 v5, v1, v64
	v_mul_f32_e32 v0, v2, v64
	v_mul_f32_e32 v1, v3, v64
	v_mul_f32_e32 v2, v66, v8
	v_mul_f32_e32 v3, v67, v9
	v_mul_f32_e32 v54, v68, v6
	v_mul_f32_e32 v55, v69, v7
	v_mul_f32_e32 v56, v70, v4
	v_mul_f32_e32 v57, v71, v5
	v_mul_f32_e32 v58, v72, v0
	v_mul_f32_e32 v59, v73, v1
	v_cvt_pk_bf16_f32 v52, v2, v3
	v_cvt_pk_bf16_f32 v53, v54, v55
	v_cvt_pk_bf16_f32 v54, v56, v57
	v_cvt_pk_bf16_f32 v55, v58, v59
	global_store_dwordx4 v[62:63], v[52:55], off offset:1024
	s_and_saveexec_b64 s[2:3], vcc
	s_cbranch_execz .LBB0_971
	v_lshl_add_u64 v[2:3], v[38:39], 0, v[176:177]
	v_lshl_add_u64 v[54:55], v[36:37], 0, v[50:51]
	global_load_dwordx4 v[36:39], v[2:3], off offset:16
	global_load_dwordx4 v[50:53], v[2:3], off
	s_waitcnt vmcnt(0)
	v_mul_f32_e32 v12, v12, v36
	v_mul_f32_e32 v13, v13, v37
	v_mul_f32_e32 v48, v48, v50
	v_mul_f32_e32 v49, v49, v51
	v_mul_f32_e32 v14, v14, v52
	v_mul_f32_e32 v15, v15, v53
	v_mul_f32_e32 v10, v10, v38
	v_mul_f32_e32 v11, v11, v39
	v_cvt_pk_bf16_f32 v48, v48, v49
	v_cvt_pk_bf16_f32 v49, v14, v15
	v_cvt_pk_bf16_f32 v50, v12, v13
	v_cvt_pk_bf16_f32 v51, v10, v11
	global_store_dwordx4 v[54:55], v[48:51], off
	global_load_dwordx4 v[10:13], v[2:3], off offset:2064
	global_load_dwordx4 v[36:39], v[2:3], off offset:2048
	s_waitcnt vmcnt(0)
	v_mul_f32_e32 v4, v4, v10
	v_mul_f32_e32 v5, v5, v11
	v_mul_f32_e32 v2, v8, v36
	v_mul_f32_e32 v3, v9, v37
	v_mul_f32_e32 v6, v6, v38
	v_mul_f32_e32 v7, v7, v39
	v_mul_f32_e32 v0, v0, v12
	v_mul_f32_e32 v1, v1, v13
	v_cvt_pk_bf16_f32 v2, v2, v3
	v_cvt_pk_bf16_f32 v3, v6, v7
	v_cvt_pk_bf16_f32 v4, v4, v5
	v_cvt_pk_bf16_f32 v5, v0, v1
	global_store_dwordx4 v[54:55], v[2:5], off offset:1024
	s_branch .LBB0_971
